# MFMA/LDS interleave in long-conv: second B fragment read together with the first (own register), one LDS round trip per 16-k group
# baseline (speedup 1.0000x reference)
; #define MFMA(a, b, c) __builtin_amdgcn_mfma_f32_32x32x16_bf16((a), (b), (c), 0, 0, 0)
; __device__ __forceinline__ void toeplitz_item(const Params& p, int layer, int half, int c, bf16* sm, int dry, unsigned* done_ctr) {
;     ...
;     for (int Dl = 0; Dl < 4; ++Dl) {
;       const int D = D0 + Dl;
;       bool actv[2];
;       int bblk[2];
; #pragma unroll
;       for (int ni = 0; ni < 2; ++ni) {
;         const int nlo = 32 * wn + 64 * ni;
;         actv[ni] = half ? true : !((nlo + 31 - D < 0) || (nlo - D >= 128));
;         const int n = nlo + r;
;         const int src = n - D;
;         const bool valid = half ? ((unsigned)((n & 15) - D) < 16u) : ((unsigned)src < 128u);
;         bblk[ni] = valid ? src : 128;
;       }
;       if (!actv[0] && !actv[1]) continue;
;       const int tb = 16 * (3 - Dl) + 16 + hh - rt;
;       const bf16* ap0 = sW + (aq * 83 + tb - 4 * (2 * wm)) * 8;
;       const bf16* bp0 = sU + bblk[0] * 136 + 8 * hh;
;       const bf16* bp1 = sU + bblk[1] * 136 + 8 * hh;
;       if (actv[0] && actv[1]) {
; #pragma unroll
;         for (int ks = 0; ks < 8; ++ks) {
;           const s8v a0 = *(const s8v*)(ap0 + 16 * ks), a1 = *(const s8v*)(ap0 - 32 + 16 * ks);
;           const s8v b0 = *(const s8v*)(bp0 + 16 * ks), b1 = *(const s8v*)(bp1 + 16 * ks);
;           acc[0][0] = MFMA(a0, b0, acc[0][0]);
;           acc[1][0] = MFMA(a1, b0, acc[1][0]);
;           acc[0][1] = MFMA(a0, b1, acc[0][1]);
;           acc[1][1] = MFMA(a1, b1, acc[1][1]);
;         }
.LBB0_1147:
	s_or_b64 exec, exec, s[2:3]
	v_add_u32_e32 v66, 3, v123
	v_add_u32_e32 v124, s74, v122
	v_cmp_gt_u32_e64 s[2:3], 16, v66
	v_add_u32_e32 v66, 0x1100, v124
	ds_read_b128 v[70:73], v89 offset:35088
	v_cndmask_b32_e64 v66, v228, v66, s[2:3]
	v_add_u32_e32 v125, v90, v66
	ds_read_b128 v[66:69], v89 offset:35024
	ds_read_b128 v[74:77], v125
	v_add_u32_e32 v78, 0x5500, v124
	s_waitcnt lgkmcnt(0)
	v_mfma_f32_32x32x16_bf16 v[50:65], v[70:73], v[74:77], v[50:65]
	s_addk_i32 s74, 0xfbc0
	s_cmpk_eq_i32 s74, 0xe240
	v_mfma_f32_32x32x16_bf16 v[18:33], v[66:69], v[74:77], v[18:33]
	v_cndmask_b32_e64 v74, v228, v78, s[2:3]
	v_add_u32_e32 v134, v90, v74
	ds_read_b128 v[74:77], v134
	ds_read_b128 v[78:81], v89 offset:35120
	ds_read_b128 v[126:129], v125 offset:32
	s_waitcnt lgkmcnt(2)
	v_mfma_f32_32x32x16_bf16 v[34:49], v[70:73], v[74:77], v[34:49]
	v_mfma_f32_32x32x16_bf16 v[2:17], v[66:69], v[74:77], v[2:17]
	ds_read_b128 v[74:77], v89 offset:35056
	s_waitcnt lgkmcnt(1)
	v_mfma_f32_32x32x16_bf16 v[50:65], v[78:81], v[126:129], v[50:65]
	s_waitcnt lgkmcnt(0)
	v_mfma_f32_32x32x16_bf16 v[18:33], v[74:77], v[126:129], v[18:33]
	ds_read_b128 v[126:129], v134 offset:32
	s_waitcnt lgkmcnt(0)
	v_mfma_f32_32x32x16_bf16 v[34:49], v[78:81], v[126:129], v[34:49]
	v_mfma_f32_32x32x16_bf16 v[2:17], v[74:77], v[126:129], v[2:17]
	ds_read_b128 v[126:129], v89 offset:35152
	ds_read_b128 v[130:133], v125 offset:64
	ds_read_b128 v[200:203], v134 offset:64
	s_waitcnt lgkmcnt(1)
	v_mfma_f32_32x32x16_bf16 v[50:65], v[126:129], v[130:133], v[50:65]
	v_mfma_f32_32x32x16_bf16 v[18:33], v[70:73], v[130:133], v[18:33]
	s_waitcnt lgkmcnt(0)
	v_mfma_f32_32x32x16_bf16 v[34:49], v[126:129], v[200:203], v[34:49]
	v_mfma_f32_32x32x16_bf16 v[2:17], v[70:73], v[200:203], v[2:17]
	ds_read_b128 v[70:73], v89 offset:35184
	ds_read_b128 v[130:133], v125 offset:96
	ds_read_b128 v[200:203], v134 offset:96
	s_waitcnt lgkmcnt(1)
	v_mfma_f32_32x32x16_bf16 v[50:65], v[70:73], v[130:133], v[50:65]
	v_mfma_f32_32x32x16_bf16 v[18:33], v[78:81], v[130:133], v[18:33]
	s_waitcnt lgkmcnt(0)
	v_mfma_f32_32x32x16_bf16 v[34:49], v[70:73], v[200:203], v[34:49]
	v_mfma_f32_32x32x16_bf16 v[2:17], v[78:81], v[200:203], v[2:17]
	ds_read_b128 v[78:81], v89 offset:35216
	ds_read_b128 v[130:133], v125 offset:128
	ds_read_b128 v[200:203], v134 offset:128
	s_waitcnt lgkmcnt(1)
	v_mfma_f32_32x32x16_bf16 v[50:65], v[78:81], v[130:133], v[50:65]
	v_mfma_f32_32x32x16_bf16 v[18:33], v[126:129], v[130:133], v[18:33]
	s_waitcnt lgkmcnt(0)
	v_mfma_f32_32x32x16_bf16 v[34:49], v[78:81], v[200:203], v[34:49]
	v_mfma_f32_32x32x16_bf16 v[2:17], v[126:129], v[200:203], v[2:17]
	ds_read_b128 v[126:129], v89 offset:35248
	ds_read_b128 v[130:133], v125 offset:160
	ds_read_b128 v[200:203], v134 offset:160
	s_waitcnt lgkmcnt(1)
	v_mfma_f32_32x32x16_bf16 v[50:65], v[126:129], v[130:133], v[50:65]
	v_mfma_f32_32x32x16_bf16 v[18:33], v[70:73], v[130:133], v[18:33]
	s_waitcnt lgkmcnt(0)
	v_mfma_f32_32x32x16_bf16 v[34:49], v[126:129], v[200:203], v[34:49]
	v_mfma_f32_32x32x16_bf16 v[2:17], v[70:73], v[200:203], v[2:17]
	ds_read_b128 v[70:73], v89 offset:35280
	ds_read_b128 v[130:133], v125 offset:192
	ds_read_b128 v[200:203], v134 offset:192
	s_waitcnt lgkmcnt(1)
	v_mfma_f32_32x32x16_bf16 v[50:65], v[70:73], v[130:133], v[50:65]
	v_mfma_f32_32x32x16_bf16 v[18:33], v[78:81], v[130:133], v[18:33]
	s_waitcnt lgkmcnt(0)
	v_mfma_f32_32x32x16_bf16 v[34:49], v[70:73], v[200:203], v[34:49]
	v_mfma_f32_32x32x16_bf16 v[2:17], v[78:81], v[200:203], v[2:17]
	ds_read_b128 v[70:73], v89 offset:35312
	ds_read_b128 v[78:81], v125 offset:224
	v_add_u32_e32 v130, 0x53f0, v124
	s_waitcnt lgkmcnt(0)
	v_mfma_f32_32x32x16_bf16 v[50:65], v[70:73], v[78:81], v[50:65]
	v_mfma_f32_32x32x16_bf16 v[18:33], v[126:129], v[78:81], v[18:33]
	ds_read_b128 v[78:81], v134 offset:224
	s_waitcnt lgkmcnt(0)
	v_mfma_f32_32x32x16_bf16 v[34:49], v[70:73], v[78:81], v[34:49]
	v_add_u32_e32 v70, 2, v123
	v_cmp_gt_u32_e64 s[2:3], 16, v70
	v_add_u32_e32 v70, 0xff0, v124
	s_nop 0
	v_cndmask_b32_e64 v70, v228, v70, s[2:3]
	v_add_u32_e32 v125, v90, v70
	ds_read_b128 v[70:73], v89 offset:34768
	v_mfma_f32_32x32x16_bf16 v[2:17], v[126:129], v[78:81], v[2:17]
	ds_read_b128 v[126:129], v89 offset:34832
	ds_read_b128 v[78:81], v125
	s_waitcnt lgkmcnt(0)
	v_mfma_f32_32x32x16_bf16 v[50:65], v[126:129], v[78:81], v[50:65]
	v_mfma_f32_32x32x16_bf16 v[18:33], v[70:73], v[78:81], v[18:33]
	v_cndmask_b32_e64 v78, v228, v130, s[2:3]
	v_add_u32_e32 v142, v90, v78
	ds_read_b128 v[78:81], v142
	ds_read_b128 v[130:133], v89 offset:34864
	ds_read_b128 v[134:137], v125 offset:32
	s_waitcnt lgkmcnt(2)
	v_mfma_f32_32x32x16_bf16 v[34:49], v[126:129], v[78:81], v[34:49]
	v_mfma_f32_32x32x16_bf16 v[2:17], v[70:73], v[78:81], v[2:17]
	ds_read_b128 v[78:81], v89 offset:34800
	s_waitcnt lgkmcnt(1)
	v_mfma_f32_32x32x16_bf16 v[50:65], v[130:133], v[134:137], v[50:65]
	s_waitcnt lgkmcnt(0)
	v_mfma_f32_32x32x16_bf16 v[18:33], v[78:81], v[134:137], v[18:33]
	ds_read_b128 v[134:137], v142 offset:32
	s_waitcnt lgkmcnt(0)
	v_mfma_f32_32x32x16_bf16 v[34:49], v[130:133], v[134:137], v[34:49]
	v_mfma_f32_32x32x16_bf16 v[2:17], v[78:81], v[134:137], v[2:17]
	ds_read_b128 v[134:137], v89 offset:34896
	ds_read_b128 v[138:141], v125 offset:64
	ds_read_b128 v[200:203], v142 offset:64
	s_waitcnt lgkmcnt(1)
	v_mfma_f32_32x32x16_bf16 v[50:65], v[134:137], v[138:141], v[50:65]
	v_mfma_f32_32x32x16_bf16 v[18:33], v[126:129], v[138:141], v[18:33]
	s_waitcnt lgkmcnt(0)
	v_mfma_f32_32x32x16_bf16 v[34:49], v[134:137], v[200:203], v[34:49]
	v_mfma_f32_32x32x16_bf16 v[2:17], v[126:129], v[200:203], v[2:17]
	ds_read_b128 v[126:129], v89 offset:34928
	ds_read_b128 v[138:141], v125 offset:96
	ds_read_b128 v[200:203], v142 offset:96
	s_waitcnt lgkmcnt(1)
; #define MFMA(a, b, c) __builtin_amdgcn_mfma_f32_32x32x16_bf16((a), (b), (c), 0, 0, 0)
; __device__ __forceinline__ void toeplitz_item(const Params& p, int layer, int half, int c, bf16* sm, int dry, unsigned* done_ctr) {
;     ...
;     for (int Dl = 0; Dl < 4; ++Dl) {
;       const int D = D0 + Dl;
;       bool actv[2];
;       int bblk[2];
; #pragma unroll
;       for (int ni = 0; ni < 2; ++ni) {
;         const int nlo = 32 * wn + 64 * ni;
;         actv[ni] = half ? true : !((nlo + 31 - D < 0) || (nlo - D >= 128));
;         const int n = nlo + r;
;         const int src = n - D;
;         const bool valid = half ? ((unsigned)((n & 15) - D) < 16u) : ((unsigned)src < 128u);
;         bblk[ni] = valid ? src : 128;
;       }
;       if (!actv[0] && !actv[1]) continue;
;       const int tb = 16 * (3 - Dl) + 16 + hh - rt;
;       const bf16* ap0 = sW + (aq * 83 + tb - 4 * (2 * wm)) * 8;
;       const bf16* bp0 = sU + bblk[0] * 136 + 8 * hh;
;       const bf16* bp1 = sU + bblk[1] * 136 + 8 * hh;
;       if (actv[0] && actv[1]) {
; #pragma unroll
;         for (int ks = 0; ks < 8; ++ks) {
;           const s8v a0 = *(const s8v*)(ap0 + 16 * ks), a1 = *(const s8v*)(ap0 - 32 + 16 * ks);
;           const s8v b0 = *(const s8v*)(bp0 + 16 * ks), b1 = *(const s8v*)(bp1 + 16 * ks);
;           acc[0][0] = MFMA(a0, b0, acc[0][0]);
;           acc[1][0] = MFMA(a1, b0, acc[1][0]);
;           acc[0][1] = MFMA(a0, b1, acc[0][1]);
;           acc[1][1] = MFMA(a1, b1, acc[1][1]);
;         }
	v_mfma_f32_32x32x16_bf16 v[50:65], v[126:129], v[138:141], v[50:65]
	v_mfma_f32_32x32x16_bf16 v[18:33], v[130:133], v[138:141], v[18:33]
	s_waitcnt lgkmcnt(0)
	v_mfma_f32_32x32x16_bf16 v[34:49], v[126:129], v[200:203], v[34:49]
	v_mfma_f32_32x32x16_bf16 v[2:17], v[130:133], v[200:203], v[2:17]
	ds_read_b128 v[130:133], v89 offset:34960
	ds_read_b128 v[138:141], v125 offset:128
	ds_read_b128 v[200:203], v142 offset:128
	s_waitcnt lgkmcnt(1)
	v_mfma_f32_32x32x16_bf16 v[50:65], v[130:133], v[138:141], v[50:65]
	v_mfma_f32_32x32x16_bf16 v[18:33], v[134:137], v[138:141], v[18:33]
	s_waitcnt lgkmcnt(0)
	v_mfma_f32_32x32x16_bf16 v[34:49], v[130:133], v[200:203], v[34:49]
	v_mfma_f32_32x32x16_bf16 v[2:17], v[134:137], v[200:203], v[2:17]
	ds_read_b128 v[134:137], v89 offset:34992
	ds_read_b128 v[138:141], v125 offset:160
	s_waitcnt lgkmcnt(0)
	v_mfma_f32_32x32x16_bf16 v[50:65], v[134:137], v[138:141], v[50:65]
	v_mfma_f32_32x32x16_bf16 v[18:33], v[126:129], v[138:141], v[18:33]
	ds_read_b128 v[138:141], v142 offset:160
	s_waitcnt lgkmcnt(0)
	v_mfma_f32_32x32x16_bf16 v[2:17], v[126:129], v[138:141], v[2:17]
	ds_read_b128 v[126:129], v125 offset:192
	v_mfma_f32_32x32x16_bf16 v[34:49], v[134:137], v[138:141], v[34:49]
	s_waitcnt lgkmcnt(0)
	v_mfma_f32_32x32x16_bf16 v[50:65], v[66:69], v[126:129], v[50:65]
	v_mfma_f32_32x32x16_bf16 v[18:33], v[130:133], v[126:129], v[18:33]
	ds_read_b128 v[126:129], v142 offset:192
	s_waitcnt lgkmcnt(0)
	v_mfma_f32_32x32x16_bf16 v[34:49], v[66:69], v[126:129], v[34:49]
	ds_read_b128 v[66:69], v125 offset:224
	v_mfma_f32_32x32x16_bf16 v[2:17], v[130:133], v[126:129], v[2:17]
	ds_read_b128 v[126:129], v89 offset:34576
	v_add_u32_e32 v130, 0x52e0, v124
	s_waitcnt lgkmcnt(1)
	v_mfma_f32_32x32x16_bf16 v[50:65], v[74:77], v[66:69], v[50:65]
	v_mfma_f32_32x32x16_bf16 v[18:33], v[134:137], v[66:69], v[18:33]
	ds_read_b128 v[66:69], v142 offset:224
	s_waitcnt lgkmcnt(0)
	v_mfma_f32_32x32x16_bf16 v[34:49], v[74:77], v[66:69], v[34:49]
	v_mfma_f32_32x32x16_bf16 v[2:17], v[134:137], v[66:69], v[2:17]
	v_add_u32_e32 v66, 1, v123
	v_cmp_gt_u32_e64 s[2:3], 16, v66
	v_add_u32_e32 v66, 0xee0, v124
	s_nop 0
	v_cndmask_b32_e64 v66, v228, v66, s[2:3]
	v_add_u32_e32 v125, v90, v66
	ds_read_b128 v[66:69], v89 offset:34512
	ds_read_b128 v[74:77], v125
	s_waitcnt lgkmcnt(0)
	v_mfma_f32_32x32x16_bf16 v[50:65], v[126:129], v[74:77], v[50:65]
	v_mfma_f32_32x32x16_bf16 v[18:33], v[66:69], v[74:77], v[18:33]
	v_cndmask_b32_e64 v74, v228, v130, s[2:3]
	v_add_u32_e32 v142, v90, v74
	ds_read_b128 v[74:77], v142
	ds_read_b128 v[130:133], v89 offset:34608
	ds_read_b128 v[134:137], v125 offset:32
	v_cmp_gt_u32_e64 s[2:3], 16, v123
	v_add_u32_e32 v123, -4, v123
	s_waitcnt lgkmcnt(2)
	v_mfma_f32_32x32x16_bf16 v[34:49], v[126:129], v[74:77], v[34:49]
	v_mfma_f32_32x32x16_bf16 v[2:17], v[66:69], v[74:77], v[2:17]
	ds_read_b128 v[74:77], v89 offset:34544
	s_waitcnt lgkmcnt(1)
	v_mfma_f32_32x32x16_bf16 v[50:65], v[130:133], v[134:137], v[50:65]
	s_waitcnt lgkmcnt(0)
	v_mfma_f32_32x32x16_bf16 v[18:33], v[74:77], v[134:137], v[18:33]
	ds_read_b128 v[134:137], v142 offset:32
	s_waitcnt lgkmcnt(0)
	v_mfma_f32_32x32x16_bf16 v[34:49], v[130:133], v[134:137], v[34:49]
	v_mfma_f32_32x32x16_bf16 v[2:17], v[74:77], v[134:137], v[2:17]
	ds_read_b128 v[134:137], v89 offset:34640
	ds_read_b128 v[138:141], v125 offset:64
	ds_read_b128 v[200:203], v142 offset:64
	s_waitcnt lgkmcnt(1)
	v_mfma_f32_32x32x16_bf16 v[50:65], v[134:137], v[138:141], v[50:65]
	v_mfma_f32_32x32x16_bf16 v[18:33], v[126:129], v[138:141], v[18:33]
	s_waitcnt lgkmcnt(0)
	v_mfma_f32_32x32x16_bf16 v[34:49], v[134:137], v[200:203], v[34:49]
	v_mfma_f32_32x32x16_bf16 v[2:17], v[126:129], v[200:203], v[2:17]
	ds_read_b128 v[126:129], v89 offset:34672
	ds_read_b128 v[138:141], v125 offset:96
	ds_read_b128 v[200:203], v142 offset:96
	s_waitcnt lgkmcnt(1)
	v_mfma_f32_32x32x16_bf16 v[50:65], v[126:129], v[138:141], v[50:65]
	v_mfma_f32_32x32x16_bf16 v[18:33], v[130:133], v[138:141], v[18:33]
	s_waitcnt lgkmcnt(0)
	v_mfma_f32_32x32x16_bf16 v[34:49], v[126:129], v[200:203], v[34:49]
	v_mfma_f32_32x32x16_bf16 v[2:17], v[130:133], v[200:203], v[2:17]
	ds_read_b128 v[130:133], v89 offset:34704
	ds_read_b128 v[138:141], v125 offset:128
	ds_read_b128 v[200:203], v142 offset:128
	s_waitcnt lgkmcnt(1)
	v_mfma_f32_32x32x16_bf16 v[50:65], v[130:133], v[138:141], v[50:65]
	v_mfma_f32_32x32x16_bf16 v[18:33], v[134:137], v[138:141], v[18:33]
	s_waitcnt lgkmcnt(0)
	v_mfma_f32_32x32x16_bf16 v[34:49], v[130:133], v[200:203], v[34:49]
	v_mfma_f32_32x32x16_bf16 v[2:17], v[134:137], v[200:203], v[2:17]
	ds_read_b128 v[134:137], v89 offset:34736
	ds_read_b128 v[138:141], v125 offset:160
	s_waitcnt lgkmcnt(0)
	v_mfma_f32_32x32x16_bf16 v[50:65], v[134:137], v[138:141], v[50:65]
	v_mfma_f32_32x32x16_bf16 v[18:33], v[126:129], v[138:141], v[18:33]
	ds_read_b128 v[138:141], v142 offset:160
	s_waitcnt lgkmcnt(0)
; #define MFMA(a, b, c) __builtin_amdgcn_mfma_f32_32x32x16_bf16((a), (b), (c), 0, 0, 0)
; __device__ __forceinline__ void toeplitz_item(const Params& p, int layer, int half, int c, bf16* sm, int dry, unsigned* done_ctr) {
;     ...
;     for (int Dl = 0; Dl < 4; ++Dl) {
;       const int D = D0 + Dl;
;       bool actv[2];
;       int bblk[2];
; #pragma unroll
;       for (int ni = 0; ni < 2; ++ni) {
;         const int nlo = 32 * wn + 64 * ni;
;         actv[ni] = half ? true : !((nlo + 31 - D < 0) || (nlo - D >= 128));
;         const int n = nlo + r;
;         const int src = n - D;
;         const bool valid = half ? ((unsigned)((n & 15) - D) < 16u) : ((unsigned)src < 128u);
;         bblk[ni] = valid ? src : 128;
;       }
;       if (!actv[0] && !actv[1]) continue;
;       const int tb = 16 * (3 - Dl) + 16 + hh - rt;
;       const bf16* ap0 = sW + (aq * 83 + tb - 4 * (2 * wm)) * 8;
;       const bf16* bp0 = sU + bblk[0] * 136 + 8 * hh;
;       const bf16* bp1 = sU + bblk[1] * 136 + 8 * hh;
;       if (actv[0] && actv[1]) {
; #pragma unroll
;         for (int ks = 0; ks < 8; ++ks) {
;           const s8v a0 = *(const s8v*)(ap0 + 16 * ks), a1 = *(const s8v*)(ap0 - 32 + 16 * ks);
;           const s8v b0 = *(const s8v*)(bp0 + 16 * ks), b1 = *(const s8v*)(bp1 + 16 * ks);
;           acc[0][0] = MFMA(a0, b0, acc[0][0]);
;           acc[1][0] = MFMA(a1, b0, acc[1][0]);
;           acc[0][1] = MFMA(a0, b1, acc[0][1]);
;           acc[1][1] = MFMA(a1, b1, acc[1][1]);
;         }
	v_mfma_f32_32x32x16_bf16 v[2:17], v[126:129], v[138:141], v[2:17]
	ds_read_b128 v[126:129], v125 offset:192
	v_mfma_f32_32x32x16_bf16 v[34:49], v[134:137], v[138:141], v[34:49]
	s_waitcnt lgkmcnt(0)
	v_mfma_f32_32x32x16_bf16 v[50:65], v[70:73], v[126:129], v[50:65]
	v_mfma_f32_32x32x16_bf16 v[18:33], v[130:133], v[126:129], v[18:33]
	ds_read_b128 v[126:129], v142 offset:192
	s_waitcnt lgkmcnt(0)
	v_mfma_f32_32x32x16_bf16 v[34:49], v[70:73], v[126:129], v[34:49]
	ds_read_b128 v[70:73], v125 offset:224
	v_mfma_f32_32x32x16_bf16 v[2:17], v[130:133], v[126:129], v[2:17]
	ds_read_b128 v[126:129], v89 offset:34256
	s_waitcnt lgkmcnt(1)
	v_mfma_f32_32x32x16_bf16 v[50:65], v[78:81], v[70:73], v[50:65]
	v_mfma_f32_32x32x16_bf16 v[18:33], v[134:137], v[70:73], v[18:33]
	ds_read_b128 v[70:73], v142 offset:224
	s_waitcnt lgkmcnt(0)
	v_mfma_f32_32x32x16_bf16 v[34:49], v[78:81], v[70:73], v[34:49]
	v_add_u32_e32 v78, 0xdd0, v124
	v_cndmask_b32_e64 v78, v228, v78, s[2:3]
	v_add_u32_e32 v132, v90, v78
	ds_read_b128 v[78:81], v132
	v_add_u32_e32 v124, 0x51d0, v124
	v_mfma_f32_32x32x16_bf16 v[2:17], v[134:137], v[70:73], v[2:17]
	ds_read_b128 v[70:73], v89 offset:34320
	s_waitcnt lgkmcnt(0)
	v_mfma_f32_32x32x16_bf16 v[50:65], v[70:73], v[78:81], v[50:65]
	v_mfma_f32_32x32x16_bf16 v[18:33], v[126:129], v[78:81], v[18:33]
	v_cndmask_b32_e64 v78, v228, v124, s[2:3]
	v_add_u32_e32 v133, v90, v78
	ds_read_b128 v[78:81], v133
	s_movk_i32 s2, 0xfc00
	s_mov_b32 s3, -1
	v_lshl_add_u64 v[82:83], v[82:83], 0, s[2:3]
	v_lshl_add_u64 v[84:85], v[84:85], 0, s[2:3]
	s_waitcnt lgkmcnt(0)
	v_mfma_f32_32x32x16_bf16 v[34:49], v[70:73], v[78:81], v[34:49]
	v_lshl_add_u64 v[86:87], v[86:87], 0, s[2:3]
	v_mfma_f32_32x32x16_bf16 v[2:17], v[126:129], v[78:81], v[2:17]
	ds_read_b128 v[78:81], v89 offset:34352
	ds_read_b128 v[124:127], v132 offset:32
	ds_read_b128 v[128:131], v89 offset:34288
	s_waitcnt lgkmcnt(1)
	v_mfma_f32_32x32x16_bf16 v[50:65], v[78:81], v[124:127], v[50:65]
	s_waitcnt lgkmcnt(0)
	v_mfma_f32_32x32x16_bf16 v[18:33], v[128:131], v[124:127], v[18:33]
	ds_read_b128 v[124:127], v133 offset:32
	s_waitcnt lgkmcnt(0)
	v_mfma_f32_32x32x16_bf16 v[34:49], v[78:81], v[124:127], v[34:49]
	v_mfma_f32_32x32x16_bf16 v[2:17], v[128:131], v[124:127], v[2:17]
	ds_read_b128 v[124:127], v89 offset:34384
	ds_read_b128 v[128:131], v132 offset:64
	ds_read_b128 v[200:203], v133 offset:64
	s_waitcnt lgkmcnt(1)
	v_mfma_f32_32x32x16_bf16 v[50:65], v[124:127], v[128:131], v[50:65]
	v_mfma_f32_32x32x16_bf16 v[18:33], v[70:73], v[128:131], v[18:33]
	s_waitcnt lgkmcnt(0)
	v_mfma_f32_32x32x16_bf16 v[34:49], v[124:127], v[200:203], v[34:49]
	v_mfma_f32_32x32x16_bf16 v[2:17], v[70:73], v[200:203], v[2:17]
	ds_read_b128 v[70:73], v89 offset:34416
	ds_read_b128 v[128:131], v132 offset:96
	ds_read_b128 v[200:203], v133 offset:96
	s_waitcnt lgkmcnt(1)
	v_mfma_f32_32x32x16_bf16 v[50:65], v[70:73], v[128:131], v[50:65]
	v_mfma_f32_32x32x16_bf16 v[18:33], v[78:81], v[128:131], v[18:33]
	s_waitcnt lgkmcnt(0)
	v_mfma_f32_32x32x16_bf16 v[34:49], v[70:73], v[200:203], v[34:49]
	v_mfma_f32_32x32x16_bf16 v[2:17], v[78:81], v[200:203], v[2:17]
	ds_read_b128 v[78:81], v89 offset:34448
	ds_read_b128 v[128:131], v132 offset:128
	ds_read_b128 v[200:203], v133 offset:128
	s_waitcnt lgkmcnt(1)
	v_mfma_f32_32x32x16_bf16 v[50:65], v[78:81], v[128:131], v[50:65]
	v_mfma_f32_32x32x16_bf16 v[18:33], v[124:127], v[128:131], v[18:33]
	s_waitcnt lgkmcnt(0)
	v_mfma_f32_32x32x16_bf16 v[34:49], v[78:81], v[200:203], v[34:49]
	v_mfma_f32_32x32x16_bf16 v[2:17], v[124:127], v[200:203], v[2:17]
	ds_read_b128 v[124:127], v89 offset:34480
	ds_read_b128 v[128:131], v132 offset:160
	s_waitcnt lgkmcnt(0)
	v_mfma_f32_32x32x16_bf16 v[50:65], v[124:127], v[128:131], v[50:65]
	v_mfma_f32_32x32x16_bf16 v[18:33], v[70:73], v[128:131], v[18:33]
	ds_read_b128 v[128:131], v133 offset:160
	s_waitcnt lgkmcnt(0)
	v_mfma_f32_32x32x16_bf16 v[2:17], v[70:73], v[128:131], v[2:17]
	ds_read_b128 v[70:73], v132 offset:192
	v_mfma_f32_32x32x16_bf16 v[34:49], v[124:127], v[128:131], v[34:49]
	s_waitcnt lgkmcnt(0)
	v_mfma_f32_32x32x16_bf16 v[50:65], v[66:69], v[70:73], v[50:65]
	v_mfma_f32_32x32x16_bf16 v[18:33], v[78:81], v[70:73], v[18:33]
	ds_read_b128 v[70:73], v133 offset:192
	s_waitcnt lgkmcnt(0)
	v_mfma_f32_32x32x16_bf16 v[34:49], v[66:69], v[70:73], v[34:49]
	ds_read_b128 v[66:69], v132 offset:224
	v_mfma_f32_32x32x16_bf16 v[2:17], v[78:81], v[70:73], v[2:17]
	s_waitcnt lgkmcnt(0)
	v_mfma_f32_32x32x16_bf16 v[50:65], v[74:77], v[66:69], v[50:65]
	v_mfma_f32_32x32x16_bf16 v[18:33], v[124:127], v[66:69], v[18:33]
	ds_read_b128 v[66:69], v133 offset:224
	s_waitcnt lgkmcnt(0)
	v_mfma_f32_32x32x16_bf16 v[34:49], v[74:77], v[66:69], v[34:49]
	v_mfma_f32_32x32x16_bf16 v[2:17], v[124:127], v[66:69], v[2:17]
	s_cbranch_scc1 .LBB0_1205

; #define MFMA(a, b, c) __builtin_amdgcn_mfma_f32_32x32x16_bf16((a), (b), (c), 0, 0, 0)
; __device__ __forceinline__ void toeplitz_item(const Params& p, int layer, int half, int c, bf16* sm, int dry, unsigned* done_ctr) {
;     ...
;       if (actv[0] && actv[1]) {
; #pragma unroll
;         for (int ks = 0; ks < 8; ++ks) {
;           const s8v a0 = *(const s8v*)(ap0 + 16 * ks), a1 = *(const s8v*)(ap0 - 32 + 16 * ks);
;           const s8v b0 = *(const s8v*)(bp0 + 16 * ks), b1 = *(const s8v*)(bp1 + 16 * ks);
;           acc[0][0] = MFMA(a0, b0, acc[0][0]);
;           acc[1][0] = MFMA(a1, b0, acc[1][0]);
;           acc[0][1] = MFMA(a0, b1, acc[0][1]);
;           acc[1][1] = MFMA(a1, b1, acc[1][1]);
;         }
.LBB0_1429:
	s_andn2_saveexec_b64 s[94:95], s[20:21]
	s_cbranch_execz .LBB0_1431
	v_add_u32_e32 v14, v106, v14
	s_waitcnt lgkmcnt(0)
	ds_read_b128 v[6:9], v14
	v_add_u32_e32 v15, v106, v15
	s_waitcnt lgkmcnt(0)
	v_mfma_f32_32x32x16_bf16 v[64:79], v[2:5], v[6:9], v[64:79]
	v_mfma_f32_32x32x16_bf16 v[32:47], v[84:87], v[6:9], v[32:47]
	ds_read_b128 v[6:9], v15
	s_waitcnt lgkmcnt(0)
	v_mfma_f32_32x32x16_bf16 v[48:63], v[2:5], v[6:9], v[48:63]
	v_mfma_f32_32x32x16_bf16 v[16:31], v[84:87], v[6:9], v[16:31]
	ds_read_b128 v[6:9], v108 offset:35120
	ds_read_b128 v[10:13], v14 offset:32
	ds_read_b128 v[80:83], v108 offset:35056
	s_waitcnt lgkmcnt(1)
	v_mfma_f32_32x32x16_bf16 v[64:79], v[6:9], v[10:13], v[64:79]
	s_waitcnt lgkmcnt(0)
	v_mfma_f32_32x32x16_bf16 v[32:47], v[80:83], v[10:13], v[32:47]
	ds_read_b128 v[10:13], v15 offset:32
	s_waitcnt lgkmcnt(0)
	v_mfma_f32_32x32x16_bf16 v[48:63], v[6:9], v[10:13], v[48:63]
	v_mfma_f32_32x32x16_bf16 v[16:31], v[80:83], v[10:13], v[16:31]
	ds_read_b128 v[10:13], v108 offset:35152
	ds_read_b128 v[80:83], v14 offset:64
	ds_read_b128 v[200:203], v15 offset:64
	s_waitcnt lgkmcnt(1)
	v_mfma_f32_32x32x16_bf16 v[64:79], v[10:13], v[80:83], v[64:79]
	v_mfma_f32_32x32x16_bf16 v[32:47], v[2:5], v[80:83], v[32:47]
	s_waitcnt lgkmcnt(0)
	v_mfma_f32_32x32x16_bf16 v[48:63], v[10:13], v[200:203], v[48:63]
	v_mfma_f32_32x32x16_bf16 v[16:31], v[2:5], v[200:203], v[16:31]
	ds_read_b128 v[2:5], v108 offset:35184
	ds_read_b128 v[80:83], v14 offset:96
	ds_read_b128 v[200:203], v15 offset:96
	s_waitcnt lgkmcnt(1)
	v_mfma_f32_32x32x16_bf16 v[64:79], v[2:5], v[80:83], v[64:79]
	v_mfma_f32_32x32x16_bf16 v[32:47], v[6:9], v[80:83], v[32:47]
	s_waitcnt lgkmcnt(0)
	v_mfma_f32_32x32x16_bf16 v[48:63], v[2:5], v[200:203], v[48:63]
	v_mfma_f32_32x32x16_bf16 v[16:31], v[6:9], v[200:203], v[16:31]
	ds_read_b128 v[6:9], v108 offset:35216
	ds_read_b128 v[80:83], v14 offset:128
	ds_read_b128 v[200:203], v15 offset:128
	s_waitcnt lgkmcnt(1)
	v_mfma_f32_32x32x16_bf16 v[64:79], v[6:9], v[80:83], v[64:79]
	v_mfma_f32_32x32x16_bf16 v[32:47], v[10:13], v[80:83], v[32:47]
	s_waitcnt lgkmcnt(0)
	v_mfma_f32_32x32x16_bf16 v[48:63], v[6:9], v[200:203], v[48:63]
	v_mfma_f32_32x32x16_bf16 v[16:31], v[10:13], v[200:203], v[16:31]
	ds_read_b128 v[10:13], v108 offset:35248
	ds_read_b128 v[80:83], v14 offset:160
	ds_read_b128 v[200:203], v15 offset:160
	s_waitcnt lgkmcnt(1)
	v_mfma_f32_32x32x16_bf16 v[64:79], v[10:13], v[80:83], v[64:79]
	v_mfma_f32_32x32x16_bf16 v[32:47], v[2:5], v[80:83], v[32:47]
	s_waitcnt lgkmcnt(0)
	v_mfma_f32_32x32x16_bf16 v[48:63], v[10:13], v[200:203], v[48:63]
	v_mfma_f32_32x32x16_bf16 v[16:31], v[2:5], v[200:203], v[16:31]
	ds_read_b128 v[2:5], v108 offset:35280
	ds_read_b128 v[80:83], v14 offset:192
	s_waitcnt lgkmcnt(0)
	v_mfma_f32_32x32x16_bf16 v[64:79], v[2:5], v[80:83], v[64:79]
	v_mfma_f32_32x32x16_bf16 v[32:47], v[6:9], v[80:83], v[32:47]
	ds_read_b128 v[80:83], v15 offset:192
	s_waitcnt lgkmcnt(0)
	v_mfma_f32_32x32x16_bf16 v[48:63], v[2:5], v[80:83], v[48:63]
	v_mfma_f32_32x32x16_bf16 v[16:31], v[6:9], v[80:83], v[16:31]
	ds_read_b128 v[2:5], v108 offset:35312
	ds_read_b128 v[6:9], v14 offset:224
	s_waitcnt lgkmcnt(0)
	v_mfma_f32_32x32x16_bf16 v[64:79], v[2:5], v[6:9], v[64:79]
	v_mfma_f32_32x32x16_bf16 v[32:47], v[10:13], v[6:9], v[32:47]
	ds_read_b128 v[6:9], v15 offset:224
	s_waitcnt lgkmcnt(0)
	v_mfma_f32_32x32x16_bf16 v[48:63], v[2:5], v[6:9], v[48:63]
	v_mfma_f32_32x32x16_bf16 v[16:31], v[10:13], v[6:9], v[16:31]

; #define MFMA(a, b, c) __builtin_amdgcn_mfma_f32_32x32x16_bf16((a), (b), (c), 0, 0, 0)
; __device__ __forceinline__ void toeplitz_item(const Params& p, int layer, int half, int c, bf16* sm, int dry, unsigned* done_ctr) {
;     ...
;       if (actv[0] && actv[1]) {
; #pragma unroll
;         for (int ks = 0; ks < 8; ++ks) {
;           const s8v a0 = *(const s8v*)(ap0 + 16 * ks), a1 = *(const s8v*)(ap0 - 32 + 16 * ks);
;           const s8v b0 = *(const s8v*)(bp0 + 16 * ks), b1 = *(const s8v*)(bp1 + 16 * ks);
;           acc[0][0] = MFMA(a0, b0, acc[0][0]);
;           acc[1][0] = MFMA(a1, b0, acc[1][0]);
;           acc[0][1] = MFMA(a0, b1, acc[0][1]);
;           acc[1][1] = MFMA(a1, b1, acc[1][1]);
;         }
.LBB0_1439:
	s_andn2_saveexec_b64 s[20:21], s[20:21]
	s_cbranch_execz .LBB0_1441
	v_add_u32_e32 v14, v106, v14
	s_waitcnt lgkmcnt(0)
	ds_read_b128 v[6:9], v14
	v_add_u32_e32 v15, v106, v15
	s_waitcnt lgkmcnt(0)
	v_mfma_f32_32x32x16_bf16 v[64:79], v[2:5], v[6:9], v[64:79]
	v_mfma_f32_32x32x16_bf16 v[32:47], v[84:87], v[6:9], v[32:47]
	ds_read_b128 v[6:9], v15
	s_waitcnt lgkmcnt(0)
	v_mfma_f32_32x32x16_bf16 v[48:63], v[2:5], v[6:9], v[48:63]
	v_mfma_f32_32x32x16_bf16 v[16:31], v[84:87], v[6:9], v[16:31]
	ds_read_b128 v[6:9], v108 offset:34864
	ds_read_b128 v[10:13], v14 offset:32
	ds_read_b128 v[80:83], v108 offset:34800
	s_waitcnt lgkmcnt(1)
	v_mfma_f32_32x32x16_bf16 v[64:79], v[6:9], v[10:13], v[64:79]
	s_waitcnt lgkmcnt(0)
	v_mfma_f32_32x32x16_bf16 v[32:47], v[80:83], v[10:13], v[32:47]
	ds_read_b128 v[10:13], v15 offset:32
	s_waitcnt lgkmcnt(0)
	v_mfma_f32_32x32x16_bf16 v[48:63], v[6:9], v[10:13], v[48:63]
	v_mfma_f32_32x32x16_bf16 v[16:31], v[80:83], v[10:13], v[16:31]
	ds_read_b128 v[10:13], v108 offset:34896
	ds_read_b128 v[80:83], v14 offset:64
	ds_read_b128 v[200:203], v15 offset:64
	s_waitcnt lgkmcnt(1)
	v_mfma_f32_32x32x16_bf16 v[64:79], v[10:13], v[80:83], v[64:79]
	v_mfma_f32_32x32x16_bf16 v[32:47], v[2:5], v[80:83], v[32:47]
	s_waitcnt lgkmcnt(0)
	v_mfma_f32_32x32x16_bf16 v[48:63], v[10:13], v[200:203], v[48:63]
	v_mfma_f32_32x32x16_bf16 v[16:31], v[2:5], v[200:203], v[16:31]
	ds_read_b128 v[2:5], v108 offset:34928
	ds_read_b128 v[80:83], v14 offset:96
	ds_read_b128 v[200:203], v15 offset:96
	s_waitcnt lgkmcnt(1)
	v_mfma_f32_32x32x16_bf16 v[64:79], v[2:5], v[80:83], v[64:79]
	v_mfma_f32_32x32x16_bf16 v[32:47], v[6:9], v[80:83], v[32:47]
	s_waitcnt lgkmcnt(0)
	v_mfma_f32_32x32x16_bf16 v[48:63], v[2:5], v[200:203], v[48:63]
	v_mfma_f32_32x32x16_bf16 v[16:31], v[6:9], v[200:203], v[16:31]
	ds_read_b128 v[6:9], v108 offset:34960
	ds_read_b128 v[80:83], v14 offset:128
	ds_read_b128 v[200:203], v15 offset:128
	s_waitcnt lgkmcnt(1)
	v_mfma_f32_32x32x16_bf16 v[64:79], v[6:9], v[80:83], v[64:79]
	v_mfma_f32_32x32x16_bf16 v[32:47], v[10:13], v[80:83], v[32:47]
	s_waitcnt lgkmcnt(0)
	v_mfma_f32_32x32x16_bf16 v[48:63], v[6:9], v[200:203], v[48:63]
	v_mfma_f32_32x32x16_bf16 v[16:31], v[10:13], v[200:203], v[16:31]
	ds_read_b128 v[10:13], v108 offset:34992
	ds_read_b128 v[80:83], v14 offset:160
	ds_read_b128 v[200:203], v15 offset:160
	s_waitcnt lgkmcnt(1)
	v_mfma_f32_32x32x16_bf16 v[64:79], v[10:13], v[80:83], v[64:79]
	v_mfma_f32_32x32x16_bf16 v[32:47], v[2:5], v[80:83], v[32:47]
	s_waitcnt lgkmcnt(0)
	v_mfma_f32_32x32x16_bf16 v[48:63], v[10:13], v[200:203], v[48:63]
	v_mfma_f32_32x32x16_bf16 v[16:31], v[2:5], v[200:203], v[16:31]
	ds_read_b128 v[2:5], v108 offset:35024
	ds_read_b128 v[80:83], v14 offset:192
	s_waitcnt lgkmcnt(0)
	v_mfma_f32_32x32x16_bf16 v[64:79], v[2:5], v[80:83], v[64:79]
	v_mfma_f32_32x32x16_bf16 v[32:47], v[6:9], v[80:83], v[32:47]
	ds_read_b128 v[80:83], v15 offset:192
	s_waitcnt lgkmcnt(0)
	v_mfma_f32_32x32x16_bf16 v[48:63], v[2:5], v[80:83], v[48:63]
	v_mfma_f32_32x32x16_bf16 v[16:31], v[6:9], v[80:83], v[16:31]
	ds_read_b128 v[2:5], v108 offset:35056
	ds_read_b128 v[6:9], v14 offset:224
	s_waitcnt lgkmcnt(0)
	v_mfma_f32_32x32x16_bf16 v[64:79], v[2:5], v[6:9], v[64:79]
	v_mfma_f32_32x32x16_bf16 v[32:47], v[10:13], v[6:9], v[32:47]
	ds_read_b128 v[6:9], v15 offset:224
	s_waitcnt lgkmcnt(0)
	v_mfma_f32_32x32x16_bf16 v[48:63], v[2:5], v[6:9], v[48:63]
	v_mfma_f32_32x32x16_bf16 v[16:31], v[10:13], v[6:9], v[16:31]

; #define MFMA(a, b, c) __builtin_amdgcn_mfma_f32_32x32x16_bf16((a), (b), (c), 0, 0, 0)
; __device__ __forceinline__ void toeplitz_item(const Params& p, int layer, int half, int c, bf16* sm, int dry, unsigned* done_ctr) {
;     ...
;       if (actv[0] && actv[1]) {
; #pragma unroll
;         for (int ks = 0; ks < 8; ++ks) {
;           const s8v a0 = *(const s8v*)(ap0 + 16 * ks), a1 = *(const s8v*)(ap0 - 32 + 16 * ks);
;           const s8v b0 = *(const s8v*)(bp0 + 16 * ks), b1 = *(const s8v*)(bp1 + 16 * ks);
;           acc[0][0] = MFMA(a0, b0, acc[0][0]);
;           acc[1][0] = MFMA(a1, b0, acc[1][0]);
;           acc[0][1] = MFMA(a0, b1, acc[0][1]);
;           acc[1][1] = MFMA(a1, b1, acc[1][1]);
;         }
.LBB0_1449:
	s_andn2_saveexec_b64 s[20:21], s[20:21]
	s_cbranch_execz .LBB0_1451
	v_add_u32_e32 v14, v106, v14
	s_waitcnt lgkmcnt(0)
	ds_read_b128 v[6:9], v14
	v_add_u32_e32 v15, v106, v15
	s_waitcnt lgkmcnt(0)
	v_mfma_f32_32x32x16_bf16 v[64:79], v[2:5], v[6:9], v[64:79]
	v_mfma_f32_32x32x16_bf16 v[32:47], v[84:87], v[6:9], v[32:47]
	ds_read_b128 v[6:9], v15
	s_waitcnt lgkmcnt(0)
	v_mfma_f32_32x32x16_bf16 v[48:63], v[2:5], v[6:9], v[48:63]
	v_mfma_f32_32x32x16_bf16 v[16:31], v[84:87], v[6:9], v[16:31]
	ds_read_b128 v[6:9], v108 offset:34608
	ds_read_b128 v[10:13], v14 offset:32
	ds_read_b128 v[80:83], v108 offset:34544
	s_waitcnt lgkmcnt(1)
	v_mfma_f32_32x32x16_bf16 v[64:79], v[6:9], v[10:13], v[64:79]
	s_waitcnt lgkmcnt(0)
	v_mfma_f32_32x32x16_bf16 v[32:47], v[80:83], v[10:13], v[32:47]
	ds_read_b128 v[10:13], v15 offset:32
	s_waitcnt lgkmcnt(0)
	v_mfma_f32_32x32x16_bf16 v[48:63], v[6:9], v[10:13], v[48:63]
	v_mfma_f32_32x32x16_bf16 v[16:31], v[80:83], v[10:13], v[16:31]
	ds_read_b128 v[10:13], v108 offset:34640
	ds_read_b128 v[80:83], v14 offset:64
	ds_read_b128 v[200:203], v15 offset:64
	s_waitcnt lgkmcnt(1)
	v_mfma_f32_32x32x16_bf16 v[64:79], v[10:13], v[80:83], v[64:79]
	v_mfma_f32_32x32x16_bf16 v[32:47], v[2:5], v[80:83], v[32:47]
	s_waitcnt lgkmcnt(0)
	v_mfma_f32_32x32x16_bf16 v[48:63], v[10:13], v[200:203], v[48:63]
	v_mfma_f32_32x32x16_bf16 v[16:31], v[2:5], v[200:203], v[16:31]
	ds_read_b128 v[2:5], v108 offset:34672
	ds_read_b128 v[80:83], v14 offset:96
	ds_read_b128 v[200:203], v15 offset:96
	s_waitcnt lgkmcnt(1)
	v_mfma_f32_32x32x16_bf16 v[64:79], v[2:5], v[80:83], v[64:79]
	v_mfma_f32_32x32x16_bf16 v[32:47], v[6:9], v[80:83], v[32:47]
	s_waitcnt lgkmcnt(0)
	v_mfma_f32_32x32x16_bf16 v[48:63], v[2:5], v[200:203], v[48:63]
	v_mfma_f32_32x32x16_bf16 v[16:31], v[6:9], v[200:203], v[16:31]
	ds_read_b128 v[6:9], v108 offset:34704
	ds_read_b128 v[80:83], v14 offset:128
	ds_read_b128 v[200:203], v15 offset:128
	s_waitcnt lgkmcnt(1)
	v_mfma_f32_32x32x16_bf16 v[64:79], v[6:9], v[80:83], v[64:79]
	v_mfma_f32_32x32x16_bf16 v[32:47], v[10:13], v[80:83], v[32:47]
	s_waitcnt lgkmcnt(0)
	v_mfma_f32_32x32x16_bf16 v[48:63], v[6:9], v[200:203], v[48:63]
	v_mfma_f32_32x32x16_bf16 v[16:31], v[10:13], v[200:203], v[16:31]
	ds_read_b128 v[10:13], v108 offset:34736
	ds_read_b128 v[80:83], v14 offset:160
	ds_read_b128 v[200:203], v15 offset:160
	s_waitcnt lgkmcnt(1)
	v_mfma_f32_32x32x16_bf16 v[64:79], v[10:13], v[80:83], v[64:79]
	v_mfma_f32_32x32x16_bf16 v[32:47], v[2:5], v[80:83], v[32:47]
	s_waitcnt lgkmcnt(0)
	v_mfma_f32_32x32x16_bf16 v[48:63], v[10:13], v[200:203], v[48:63]
	v_mfma_f32_32x32x16_bf16 v[16:31], v[2:5], v[200:203], v[16:31]
	ds_read_b128 v[2:5], v108 offset:34768
	ds_read_b128 v[80:83], v14 offset:192
	s_waitcnt lgkmcnt(0)
	v_mfma_f32_32x32x16_bf16 v[64:79], v[2:5], v[80:83], v[64:79]
	v_mfma_f32_32x32x16_bf16 v[32:47], v[6:9], v[80:83], v[32:47]
	ds_read_b128 v[80:83], v15 offset:192
	s_waitcnt lgkmcnt(0)
	v_mfma_f32_32x32x16_bf16 v[48:63], v[2:5], v[80:83], v[48:63]
	v_mfma_f32_32x32x16_bf16 v[16:31], v[6:9], v[80:83], v[16:31]
	ds_read_b128 v[2:5], v108 offset:34800
	ds_read_b128 v[6:9], v14 offset:224
	s_waitcnt lgkmcnt(0)
	v_mfma_f32_32x32x16_bf16 v[64:79], v[2:5], v[6:9], v[64:79]
	v_mfma_f32_32x32x16_bf16 v[32:47], v[10:13], v[6:9], v[32:47]
	ds_read_b128 v[6:9], v15 offset:224
	s_waitcnt lgkmcnt(0)
	v_mfma_f32_32x32x16_bf16 v[48:63], v[2:5], v[6:9], v[48:63]
	v_mfma_f32_32x32x16_bf16 v[16:31], v[10:13], v[6:9], v[16:31]

; #define MFMA(a, b, c) __builtin_amdgcn_mfma_f32_32x32x16_bf16((a), (b), (c), 0, 0, 0)
; __device__ __forceinline__ void toeplitz_item(const Params& p, int layer, int half, int c, bf16* sm, int dry, unsigned* done_ctr) {
;     ...
;       if (actv[0] && actv[1]) {
; #pragma unroll
;         for (int ks = 0; ks < 8; ++ks) {
;           const s8v a0 = *(const s8v*)(ap0 + 16 * ks), a1 = *(const s8v*)(ap0 - 32 + 16 * ks);
;           const s8v b0 = *(const s8v*)(bp0 + 16 * ks), b1 = *(const s8v*)(bp1 + 16 * ks);
;           acc[0][0] = MFMA(a0, b0, acc[0][0]);
;           acc[1][0] = MFMA(a1, b0, acc[1][0]);
;           acc[0][1] = MFMA(a0, b1, acc[0][1]);
;           acc[1][1] = MFMA(a1, b1, acc[1][1]);
;         }
.LBB0_1459:
	s_andn2_saveexec_b64 s[20:21], s[20:21]
	s_cbranch_execz .LBB0_1369
	v_add_u32_e32 v0, v106, v0
	s_waitcnt lgkmcnt(0)
	ds_read_b128 v[6:9], v0
	v_add_u32_e32 v14, v106, v14
	s_waitcnt lgkmcnt(0)
	v_mfma_f32_32x32x16_bf16 v[64:79], v[2:5], v[6:9], v[64:79]
	v_mfma_f32_32x32x16_bf16 v[32:47], v[84:87], v[6:9], v[32:47]
	ds_read_b128 v[6:9], v14
	s_waitcnt lgkmcnt(0)
	v_mfma_f32_32x32x16_bf16 v[48:63], v[2:5], v[6:9], v[48:63]
	v_mfma_f32_32x32x16_bf16 v[16:31], v[84:87], v[6:9], v[16:31]
	ds_read_b128 v[6:9], v108 offset:34352
	ds_read_b128 v[10:13], v0 offset:32
	ds_read_b128 v[80:83], v108 offset:34288
	s_waitcnt lgkmcnt(1)
	v_mfma_f32_32x32x16_bf16 v[64:79], v[6:9], v[10:13], v[64:79]
	s_waitcnt lgkmcnt(0)
	v_mfma_f32_32x32x16_bf16 v[32:47], v[80:83], v[10:13], v[32:47]
	ds_read_b128 v[10:13], v14 offset:32
	s_waitcnt lgkmcnt(0)
	v_mfma_f32_32x32x16_bf16 v[48:63], v[6:9], v[10:13], v[48:63]
	v_mfma_f32_32x32x16_bf16 v[16:31], v[80:83], v[10:13], v[16:31]
	ds_read_b128 v[10:13], v108 offset:34384
	ds_read_b128 v[80:83], v0 offset:64
	ds_read_b128 v[200:203], v14 offset:64
	s_waitcnt lgkmcnt(1)
	v_mfma_f32_32x32x16_bf16 v[64:79], v[10:13], v[80:83], v[64:79]
	v_mfma_f32_32x32x16_bf16 v[32:47], v[2:5], v[80:83], v[32:47]
	s_waitcnt lgkmcnt(0)
	v_mfma_f32_32x32x16_bf16 v[48:63], v[10:13], v[200:203], v[48:63]
	v_mfma_f32_32x32x16_bf16 v[16:31], v[2:5], v[200:203], v[16:31]
	ds_read_b128 v[2:5], v108 offset:34416
	ds_read_b128 v[80:83], v0 offset:96
	ds_read_b128 v[200:203], v14 offset:96
	s_waitcnt lgkmcnt(1)
	v_mfma_f32_32x32x16_bf16 v[64:79], v[2:5], v[80:83], v[64:79]
	v_mfma_f32_32x32x16_bf16 v[32:47], v[6:9], v[80:83], v[32:47]
	s_waitcnt lgkmcnt(0)
	v_mfma_f32_32x32x16_bf16 v[48:63], v[2:5], v[200:203], v[48:63]
	v_mfma_f32_32x32x16_bf16 v[16:31], v[6:9], v[200:203], v[16:31]
	ds_read_b128 v[6:9], v108 offset:34448
	ds_read_b128 v[80:83], v0 offset:128
	ds_read_b128 v[200:203], v14 offset:128
	s_waitcnt lgkmcnt(1)
	v_mfma_f32_32x32x16_bf16 v[64:79], v[6:9], v[80:83], v[64:79]
	v_mfma_f32_32x32x16_bf16 v[32:47], v[10:13], v[80:83], v[32:47]
	s_waitcnt lgkmcnt(0)
	v_mfma_f32_32x32x16_bf16 v[48:63], v[6:9], v[200:203], v[48:63]
	v_mfma_f32_32x32x16_bf16 v[16:31], v[10:13], v[200:203], v[16:31]
	ds_read_b128 v[10:13], v108 offset:34480
	ds_read_b128 v[80:83], v0 offset:160
	ds_read_b128 v[200:203], v14 offset:160
	s_waitcnt lgkmcnt(1)
	v_mfma_f32_32x32x16_bf16 v[64:79], v[10:13], v[80:83], v[64:79]
	v_mfma_f32_32x32x16_bf16 v[32:47], v[2:5], v[80:83], v[32:47]
	s_waitcnt lgkmcnt(0)
	v_mfma_f32_32x32x16_bf16 v[48:63], v[10:13], v[200:203], v[48:63]
	v_mfma_f32_32x32x16_bf16 v[16:31], v[2:5], v[200:203], v[16:31]
	ds_read_b128 v[2:5], v108 offset:34512
	ds_read_b128 v[80:83], v0 offset:192
	s_waitcnt lgkmcnt(0)
	v_mfma_f32_32x32x16_bf16 v[64:79], v[2:5], v[80:83], v[64:79]
	v_mfma_f32_32x32x16_bf16 v[32:47], v[6:9], v[80:83], v[32:47]
	ds_read_b128 v[80:83], v14 offset:192
	s_waitcnt lgkmcnt(0)
	v_mfma_f32_32x32x16_bf16 v[48:63], v[2:5], v[80:83], v[48:63]
	v_mfma_f32_32x32x16_bf16 v[16:31], v[6:9], v[80:83], v[16:31]
	ds_read_b128 v[2:5], v108 offset:34544
	ds_read_b128 v[6:9], v0 offset:224
	s_waitcnt lgkmcnt(0)
	v_mfma_f32_32x32x16_bf16 v[64:79], v[2:5], v[6:9], v[64:79]
	v_mfma_f32_32x32x16_bf16 v[32:47], v[10:13], v[6:9], v[32:47]
	ds_read_b128 v[6:9], v14 offset:224
	s_waitcnt lgkmcnt(0)
	v_mfma_f32_32x32x16_bf16 v[48:63], v[2:5], v[6:9], v[48:63]
	v_mfma_f32_32x32x16_bf16 v[16:31], v[10:13], v[6:9], v[16:31]
	s_branch .LBB0_1369
